# P8 stagger variant: four WG groups offset by 0/5/10/15us
# baseline (speedup 1.0000x reference)
.LBB0_1462:
	s_or_b64 exec, exec, s[0:1]
	s_add_u32 s8, s64, 0xac40000
	v_mov_b32_e32 v12, v162
	s_waitcnt lgkmcnt(0)
	s_barrier
	s_cselect_b32 s101, 1, 0
	s_bfe_u32 s100, s2, 0x20003
.Lp8_loop:
	s_cmp_eq_u32 s100, 0
	s_cbranch_scc1 .Lp8_nodelay
	s_sleep 127
	s_sub_u32 s100, s100, 1
	s_branch .Lp8_loop
